# c4 + out-proj LN epilogue: 8 row-statistics loads issued together; attention item prologues (band/diff/MLA): Q loads as global loads without the full wait before the first K/V tile loads
# speedup vs baseline: 1.0105x; 1.0105x over previous
; __device__ __forceinline__ int opaque_tid() { int t = threadIdx.x; asm volatile("" : "+v"(t)); return t; }
; template <int DK, int MODE, bool OUTF32> ...
;     ...
;     const int tid = opaque_tid(), wave = tid >> 6, lane = tid & 63, c = lane & 31, hi = lane >> 5;
;     const int rg = wave >> 1, kh = wave & 1;
;     const int qw0 = q0 + 32 * rg, qrow = qw0 + c, cw = qw0 >> 6;
;     int t_lo = 0;
;     if (MODE == 1) { t_lo = (q0 >> 6) - 8; if (t_lo < 0) t_lo = 0; }
;     const int t_hi = ((q0 + 127) >> 6) + 1;
;     bf16x8 qf[NKS];
; #pragma unroll
;     for (int s = 0; s < NKS; ++s) qf[s] = *(const bf16x8*)(Qh + (size_t)qrow * DK + 16 * s + 8 * hi);
;     float cq = 0.f;
;     if (MODE == 0) cq = cumh[qrow];
; #pragma unroll
;     for (int s = 0; s < NKS; ++s) asm volatile("" : "+v"(qf[s]));
;     asm volatile("" : "+v"(cq));
;     if (MODE == 1) { for (int i = tid; i < 257; i += NTHR) ((float*)(a_lds + OFF_RB))[i] = relb[i] * LOG2E; }
; template <bool NAIVE>
; __device__ __forceinline__ void attn_even_phase(const bf16_t* __restrict__ att, const float* __restrict__ cumh, const float* __restrict__ relb,
;                                                 bf16_t* __restrict__ Ob, unsigned* ctr, float* lds, const float* __restrict__ tot) {
;     ...
;                 const int j = 31 - (item >> 4), bh = item & 15, b = bh >> 3, h = bh & 7;
;                 attn_item<128, 0, false>(att + (size_t)bh * S * 128, att + EHSZ + (size_t)bh * S * 128, att + 2 * EHSZ + (size_t)bh * 128 * S,
;                                          Ob + (size_t)b * S * D + h * 128, D, j * 128, cumh + (size_t)bh * S, tot + bh * 128, SC2);
;             } else {
;                 const int r = item - 512, j = r >> 4, bh = r & 15, b = bh >> 3, h = bh & 7;
;                 attn_item<128, 1, false>(att + 3 * EHSZ + (size_t)bh * S * 128, att + 4 * EHSZ + (size_t)bh * S * 128, att + 5 * EHSZ + (size_t)bh * 128 * S,
;                                          Ob + (size_t)b * S * D + 1024 + h * 128, D, j * 128, nullptr, relb + h * 257, SC2);
.LBB0_239:
	s_movk_i32 s12, 0x1ff
	v_and_b32_e32 v194, 15, v153
	v_cmp_lt_i32_e32 vcc, s12, v153
	v_lshlrev_b32_e32 v1, 19, v194
	v_lshlrev_b32_e32 v2, 20, v194
	v_lshlrev_b32_e32 v4, 3, v153
	s_and_saveexec_b64 s[12:13], vcc
	s_xor_b64 s[46:47], exec, s[12:13]
	s_cbranch_execz .LBB0_271
	v_mov_b32_e32 v182, v0
	v_and_b32_e32 v10, 0x7fffff80, v4
	v_add_u32_e32 v80, 0xfffff000, v10
	v_ashrrev_i32_e32 v4, 2, v182
	v_and_b32_e32 v82, 0xffffffe0, v4
	v_and_b32_e32 v81, 31, v182
	v_add_u32_e32 v84, v82, v80
	v_readlane_b32 s12, v249, 26
	v_or_b32_e32 v180, v84, v81
	v_readlane_b32 s13, v249, 27
	v_ashrrev_i32_e32 v181, 31, v180
	v_bfe_u32 v83, v182, 5, 1
	v_lshl_add_u64 v[6:7], s[12:13], 0, v[2:3]
	v_lshlrev_b64 v[4:5], 8, v[180:181]
	v_lshl_add_u64 v[4:5], v[6:7], 0, v[4:5]
	v_lshlrev_b32_e32 v68, 4, v83
	v_mov_b32_e32 v69, v3
	v_lshl_add_u64 v[4:5], v[4:5], 0, v[68:69]
	global_load_dwordx4 v[100:103], v[4:5], off
	global_load_dwordx4 v[104:107], v[4:5], off offset:32
	global_load_dwordx4 v[108:111], v[4:5], off offset:64
	global_load_dwordx4 v[112:115], v[4:5], off offset:96
	global_load_dwordx4 v[116:119], v[4:5], off offset:128
	global_load_dwordx4 v[120:123], v[4:5], off offset:160
	global_load_dwordx4 v[124:127], v[4:5], off offset:192
	global_load_dwordx4 v[128:131], v[4:5], off offset:224
	s_movk_i32 s12, 0x101
	v_and_b32_e32 v195, 7, v153
	v_mov_b32_e32 v4, v3
	v_cmp_gt_i32_e32 vcc, s12, v182
	s_and_saveexec_b64 s[40:41], vcc
	s_cbranch_execz .LBB0_248
	v_max_i32_e32 v5, 0xffffff01, v182
	v_sub_u32_e32 v5, v5, v182
	v_mul_u32_u24_e32 v4, 0x101, v195
	v_add_u32_e32 v5, 0x1ff, v5
	s_movk_i32 s12, 0x1ff
	v_cmp_lt_u32_e32 vcc, s12, v5
	s_mov_b64 s[14:15], -1
	v_lshlrev_b32_e32 v4, 2, v4
	v_mov_b32_e32 v6, v182
	s_and_saveexec_b64 s[12:13], vcc
	s_cbranch_execz .LBB0_245
	v_lshrrev_b32_e32 v5, 9, v5
	v_readlane_b32 s14, v249, 11
	v_add_u32_e32 v11, 1, v5
	v_mov_b32_e32 v5, v3
	v_readlane_b32 s15, v249, 12
	v_add_u32_e32 v183, 0x200, v182
	v_mov_b64_e32 v[8:9], v[182:183]
	v_lshl_add_u64 v[6:7], s[14:15], 0, v[4:5]
	v_and_b32_e32 v5, 0xfffffe, v11
	v_readlane_b32 s14, v248, 37
	v_mov_b32_e32 v13, v5
	s_mov_b32 s16, 0x3fb8aa3b
	v_lshl_add_u32 v12, v182, 2, s14
	s_mov_b64 s[14:15], 0

; #define LAS __attribute__((address_space(3)))
;     __device__ __forceinline__ void operator()(f32x4 (&acc)[2][2][4][2], int brow, int bcol, int wr, int wc, int fr, int fq) const {
;     ...
;         if (tid < 256) {
;             float S = 0.f, Q = 0.f;
; #pragma unroll
;             for (int c = 0; c < 8; ++c) {
;                 const unsigned long long v = __hip_atomic_load(sg + c, __ATOMIC_RELAXED, __HIP_MEMORY_SCOPE_AGENT);
;                 S += __uint_as_float((unsigned)v); Q += __uint_as_float((unsigned)(v >> 32));
;             }
;             const float mu = S * (1.f / D), var = fmaxf(Q * (1.f / D) - mu * mu, 0.f);
;             *(LAS f32x2*)((LAS unsigned char*)e_lds + 8192 + tid * 8) = f32x2{mu, rsqrtf(var + LN_EPS)};
;         }
.LBB0_376:
	s_or_b64 exec, exec, s[42:43]
	s_waitcnt lgkmcnt(0)
	s_barrier
	s_and_saveexec_b64 s[40:41], vcc
	s_cbranch_execz .LBB0_355
	global_load_dwordx2 v[14:15], v[10:11], off sc1
	global_load_dwordx2 v[18:19], v[10:11], off offset:8 sc1
	global_load_dwordx2 v[244:245], v[10:11], off offset:16 sc1
	global_load_dwordx2 v[246:247], v[10:11], off offset:24 sc1
	global_load_dwordx2 v[250:251], v[10:11], off offset:32 sc1
	global_load_dwordx2 v[252:253], v[10:11], off offset:40 sc1
	global_load_dwordx2 v[254:255], v[10:11], off offset:48 sc1
	global_load_dwordx2 v[10:11], v[10:11], off offset:56 sc1
	s_mov_b32 s12, 0x3a000000
	v_lshl_add_u32 v2, v2, 3, 0
	s_waitcnt vmcnt(7)
	v_add_f32_e32 v14, 0, v14
	v_add_f32_e32 v15, 0, v15
	s_waitcnt vmcnt(6)
	v_add_f32_e32 v14, v14, v18
	v_add_f32_e32 v15, v15, v19
	s_waitcnt vmcnt(5)
	v_add_f32_e32 v14, v14, v244
	v_add_f32_e32 v15, v15, v245
	s_waitcnt vmcnt(4)
	v_add_f32_e32 v14, v14, v246
	v_add_f32_e32 v15, v15, v247
	s_waitcnt vmcnt(3)
	v_add_f32_e32 v14, v14, v250
	v_add_f32_e32 v15, v15, v251
	s_waitcnt vmcnt(2)
	v_add_f32_e32 v14, v14, v252
	v_add_f32_e32 v15, v15, v253
	s_waitcnt vmcnt(1)
	v_add_f32_e32 v14, v14, v254
	v_add_f32_e32 v15, v15, v255
	s_waitcnt vmcnt(0)
	v_add_f32_e32 v10, v14, v10
	v_mul_f32_e32 v10, 0x3a000000, v10
	v_add_f32_e32 v11, v15, v11
	v_mul_f32_e32 v14, v10, v10
	v_fma_f32 v11, v11, s12, -v14
	v_max_f32_e32 v11, 0, v11
	v_add_f32_e32 v11, 0x3727c5ac, v11
	v_cmp_gt_f32_e32 vcc, s33, v11
	v_mul_f32_e32 v14, 0x4b800000, v11
	s_nop 0
	v_cndmask_b32_e32 v11, v11, v14, vcc
	v_rsq_f32_e32 v11, v11
	s_nop 0
	v_mul_f32_e32 v14, 0x45800000, v11
	v_cndmask_b32_e32 v11, v11, v14, vcc
	ds_write_b64 v2, v[10:11] offset:8192
	s_branch .LBB0_355

; template <int DK, int MODE, bool OUTF32> ...
;     ...
;     const int tid = opaque_tid(), wave = tid >> 6, lane = tid & 63, c = lane & 31, hi = lane >> 5;
;     const int rg = wave >> 1, kh = wave & 1;
;     const int qw0 = q0 + 32 * rg, qrow = qw0 + c, cw = qw0 >> 6;
;     int t_lo = 0;
;     if (MODE == 1) { t_lo = (q0 >> 6) - 8; if (t_lo < 0) t_lo = 0; }
;     const int t_hi = ((q0 + 127) >> 6) + 1;
;     bf16x8 qf[NKS];
; #pragma unroll
;     for (int s = 0; s < NKS; ++s) qf[s] = *(const bf16x8*)(Qh + (size_t)qrow * DK + 16 * s + 8 * hi);
;     float cq = 0.f;
;     if (MODE == 0) cq = cumh[qrow];
; #pragma unroll
;     for (int s = 0; s < NKS; ++s) asm volatile("" : "+v"(qf[s]));
;     asm volatile("" : "+v"(cq));
;     if (MODE == 1) { for (int i = tid; i < 257; i += NTHR) ((float*)(a_lds + OFF_RB))[i] = relb[i] * LOG2E; }
;     float cso = 0.f;
;     const float* offs = (const float*)(a_lds + OFF_RB);
;     if (MODE == 0) {
;         if (wave == 0) {
;             const float v0 = relb[lane], v1 = relb[64 + lane];
;             float s0 = v0, s1 = v1;
; #pragma unroll
;             for (int d_ = 1; d_ < 64; d_ <<= 1) {
;                 const float t0 = __int_as_float(__builtin_amdgcn_ds_bpermute((lane - d_) * 4, __float_as_int(s0)));
; __device__ __forceinline__ void attn_odd_phase(const bf16_t* __restrict__ att, bf16_t* __restrict__ Ob, float* __restrict__ A12, unsigned* ctr) {
;     ...
;         const int j = 31 - item / 48, r = item % 48;
;         if (r < 16) {
;             const int bh = r, b = bh >> 3, h = bh & 7;
;             attn_item<192, 2, false>(att + (size_t)bh * S * 192, att + MHSZ + (size_t)bh * S * 192, att + 2 * MHSZ + (size_t)bh * 128 * S,
;                                      Ob + (size_t)b * S * D + h * 128, D, j * 128, nullptr, nullptr, SC192);
;         } else {
;             const int v = r - 16, b = v >> 4, vh2 = v & 15, vh = vh2 >> 1, half = vh2 & 1, hd = vh >> 1, comp = vh & 1;
;             attn_item<128, 2, true>(att + 2 * MHSZ + EHSZ + (size_t)(b * 8 + vh) * S * 128, att + 2 * MHSZ + 2 * EHSZ + (size_t)(b * 8 + vh) * S * 128,
;                                     att + 2 * MHSZ + 3 * EHSZ + ((size_t)(b * 4 + hd) * 256 + half * 128) * S,
;                                     A12 + (size_t)b * S * D + hd * 512 + comp * 256 + half * 128, D, j * 128, nullptr, nullptr, SC128);
.LBB0_939:
	s_mov_b32 s12, 0xd5555555
	v_mul_hi_i32 v2, v1, s12
	v_lshrrev_b32_e32 v4, 31, v2
	v_ashrrev_i32_e32 v2, 3, v2
	s_mov_b32 s12, 0x2aaaaaab
	v_add3_u32 v2, v2, v4, 31
	v_mul_hi_i32 v4, v1, s12
	v_lshrrev_b32_e32 v5, 31, v4
	v_lshrrev_b32_e32 v4, 3, v4
	v_add_u32_e32 v4, v4, v5
	v_mul_lo_u32 v4, v4, 48
	v_sub_u32_e32 v156, v1, v4
	v_lshlrev_b32_e32 v4, 7, v2
	v_cmp_lt_i32_e32 vcc, 15, v156
	v_lshrrev_b32_e32 v1, 6, v4
	s_and_saveexec_b64 s[12:13], vcc
	s_xor_b64 s[46:47], exec, s[12:13]
	s_cbranch_execz .LBB0_955
	v_add_u32_e32 v2, -16, v156
	v_lshrrev_b32_e32 v2, 4, v2
	v_bfe_u32 v5, v156, 1, 3
	v_mov_b32_e32 v120, v0
	v_lshl_or_b32 v6, v2, 3, v5
	v_mov_b32_e32 v7, v3
	v_ashrrev_i32_e32 v5, 2, v120
	v_and_b32_e32 v5, 0xffffffe0, v5
	v_and_b32_e32 v121, 31, v120
	v_add_u32_e32 v123, v5, v4
	v_or_b32_e32 v166, v123, v121
	v_lshlrev_b64 v[6:7], 20, v[6:7]
	v_ashrrev_i32_e32 v167, 31, v166
	v_lshl_add_u64 v[8:9], s[78:79], 0, v[6:7]
	v_bfe_u32 v122, v120, 5, 1
	v_lshlrev_b64 v[4:5], 8, v[166:167]
	v_lshl_add_u64 v[4:5], v[8:9], 0, v[4:5]
	v_lshlrev_b32_e32 v164, 4, v122
	v_mov_b32_e32 v165, v3
	v_lshl_add_u64 v[4:5], v[4:5], 0, v[164:165]
	global_load_dwordx4 v[112:115], v[4:5], off
	global_load_dwordx4 v[108:111], v[4:5], off offset:32
	global_load_dwordx4 v[104:107], v[4:5], off offset:64
	global_load_dwordx4 v[100:103], v[4:5], off offset:96
	global_load_dwordx4 v[96:99], v[4:5], off offset:128
	global_load_dwordx4 v[92:95], v[4:5], off offset:160
	global_load_dwordx4 v[88:91], v[4:5], off offset:192
	global_load_dwordx4 v[84:87], v[4:5], off offset:224
	v_lshrrev_b32_e32 v165, 1, v156
	v_lshlrev_b32_e32 v4, 7, v156
	v_bfe_u32 v169, v165, 1, 2
	v_mov_b32_e32 v5, v3
	v_and_b32_e32 v168, 0x80, v4
	v_lshl_or_b32 v4, v2, 2, v169
	v_ashrrev_i32_e32 v10, 31, v120
	v_add_u32_e32 v11, 0x200, v120
	v_lshlrev_b64 v[4:5], 21, v[4:5]
	v_lshrrev_b32_e32 v10, 28, v10
	v_ashrrev_i32_e32 v13, 31, v11
	v_mov_b32_e32 v9, v3
	v_lshlrev_b32_e32 v8, 13, v168
	v_lshl_add_u64 v[70:71], s[52:53], 0, v[6:7]
	v_lshl_add_u64 v[4:5], s[54:55], 0, v[4:5]
	v_add_u32_e32 v6, v120, v10
	v_lshrrev_b32_e32 v7, 28, v13
	v_ashrrev_i32_e32 v68, 3, v120
	v_lshl_add_u64 v[74:75], v[4:5], 0, v[8:9]
	v_and_b32_e32 v4, -16, v6
	v_add_u32_e32 v5, v11, v7
	v_ashrrev_i32_e32 v69, 31, v68
	v_ashrrev_i32_e32 v76, 4, v6
	v_sub_u32_e32 v124, v120, v4
	v_and_b32_e32 v6, -16, v5
	v_lshlrev_b32_e32 v12, 4, v120
	v_lshlrev_b64 v[72:73], 13, v[68:69]
	v_ashrrev_i32_e32 v78, 4, v5
	v_ashrrev_i32_e32 v77, 31, v76
	v_sub_u32_e32 v125, v11, v6
	v_lshlrev_b32_e32 v6, 3, v124
	v_mov_b32_e32 v171, v3
	v_and_b32_e32 v170, 0x70, v12
	v_lshl_add_u64 v[4:5], v[74:75], 0, v[72:73]
	v_lshlrev_b64 v[80:81], 8, v[76:77]
	v_ashrrev_i32_e32 v79, 31, v78
	v_ashrrev_i32_e32 v7, 31, v6
	v_lshlrev_b32_e32 v10, 3, v125
	v_lshl_add_u64 v[4:5], v[4:5], 0, v[170:171]
	v_lshl_add_u64 v[8:9], v[70:71], 0, v[80:81]
	v_lshlrev_b64 v[82:83], 8, v[78:79]
	s_mov_b32 s12, 0x80000
	v_lshlrev_b64 v[116:117], 1, v[6:7]
	v_ashrrev_i32_e32 v11, 31, v10
	v_mov_b32_e32 v14, v3
	v_add_co_u32_e32 v12, vcc, s12, v4
	v_lshl_add_u64 v[6:7], v[70:71], 0, v[82:83]
	v_lshl_add_u64 v[8:9], v[8:9], 0, v[116:117]
	v_lshlrev_b64 v[118:119], 1, v[10:11]
	v_addc_co_u32_e32 v13, vcc, 0, v5, vcc
	v_lshl_add_u64 v[6:7], v[6:7], 0, v[118:119]
	v_ashrrev_i32_e32 v171, 6, v120
	s_movk_i32 s13, 0x88
	v_and_b32_e32 v180, 1, v171
	v_mul_lo_u32 v185, v68, s13
	v_mad_u32_u24 v68, v121, s13, 0
	s_movk_i32 s13, 0x110
	v_and_b32_e32 v178, 63, v120
	v_lshlrev_b32_e32 v69, 3, v122
	global_load_dwordx4 v[52:55], v[8:9], off
	global_load_dwordx4 v[56:59], v[6:7], off
	global_load_dwordx4 v[60:63], v[4:5], off
	global_load_dwordx4 v[64:67], v[12:13], off
	v_lshlrev_b32_e32 v120, 6, v180
	v_mul_lo_u32 v188, v76, s13
	v_or_b32_e32 v72, v72, v170
	v_lshlrev_b32_e32 v189, 4, v124
	v_mov_b32_e32 v18, v3
	v_mov_b32_e32 v19, v3
	v_add3_u32 v77, 0, v185, v170
	v_lshl_or_b32 v79, v180, 5, v121
	v_add3_u32 v184, v68, v69, v120
	v_lshl_add_u64 v[68:69], v[70:71], 0, s[10:11]
	v_mul_lo_u32 v190, v78, s13
	v_lshl_add_u64 v[70:71], v[74:75], 0, v[72:73]
	v_add3_u32 v74, 0, v188, v189
	v_lshlrev_b32_e32 v191, 4, v125
	s_mov_b64 s[10:11], 0x80080
	v_mov_b32_e32 v4, v3
	v_mov_b32_e32 v5, v3
	v_mov_b32_e32 v6, v3
	v_mov_b32_e32 v7, v3
	v_mov_b32_e32 v8, v3
	v_mov_b32_e32 v9, v3
	v_mov_b32_e32 v10, v3
	v_mov_b32_e32 v11, v3
	v_mov_b32_e32 v12, v3
	v_mov_b32_e32 v13, v3
	v_mov_b32_e32 v14, v3
	v_mov_b32_e32 v15, v3
	v_mov_b32_e32 v16, v3
	v_mov_b32_e32 v17, v3
	v_mov_b64_e32 v[50:51], v[18:19]
	v_mov_b64_e32 v[34:35], v[18:19]
	v_add_u32_e32 v121, 0xc800, v77
	v_add_u32_e32 v77, 0xea00, v77
	v_mul_u32_u24_e32 v79, 0x110, v79
	v_lshl_add_u64 v[172:173], v[70:71], 0, s[10:11]
	v_add3_u32 v75, 0, v190, v191
	v_lshl_add_u64 v[70:71], v[80:81], 0, v[116:117]
	v_lshl_add_u64 v[72:73], v[82:83], 0, v[118:119]
	s_mov_b32 s12, 0
	v_or_b32_e32 v182, 1, v1
	v_mov_b32_e32 v179, 0
	v_mov_b32_e32 v181, 0xf149f2ca
	s_mov_b64 s[42:43], 0
	v_mov_b64_e32 v[48:49], v[16:17]
	v_mov_b64_e32 v[46:47], v[14:15]
	v_mov_b64_e32 v[44:45], v[12:13]
	v_mov_b64_e32 v[42:43], v[10:11]
	v_mov_b64_e32 v[40:41], v[8:9]
	v_mov_b64_e32 v[38:39], v[6:7]
	v_mov_b64_e32 v[36:37], v[4:5]
	v_mov_b64_e32 v[32:33], v[16:17]
	v_mov_b64_e32 v[30:31], v[14:15]
	v_mov_b64_e32 v[28:29], v[12:13]
	v_mov_b64_e32 v[26:27], v[10:11]
	v_mov_b64_e32 v[24:25], v[8:9]
	v_mov_b64_e32 v[22:23], v[6:7]
	v_mov_b64_e32 v[20:21], v[4:5]
	v_add_u32_e32 v186, 0x2200, v185
	v_ashrrev_i32_e32 v187, 6, v123
	v_add3_u32 v183, 0, v79, v164
	v_lshl_add_u64 v[174:175], v[68:69], 0, v[70:71]
	v_lshl_add_u64 v[176:177], v[68:69], 0, v[72:73]
	s_waitcnt vmcnt(3)
	ds_write_b128 v74, v[52:55]
	s_waitcnt vmcnt(2)
	ds_write_b128 v75, v[56:59]
	s_waitcnt vmcnt(1)
	ds_write2_b64 v121, v[60:61], v[62:63] offset1:1
	s_waitcnt vmcnt(0)
	ds_write2_b64 v77, v[64:65], v[66:67] offset1:1
	v_mov_b64_e32 v[66:67], v[18:19]
	v_mov_b64_e32 v[64:65], v[16:17]
	v_mov_b64_e32 v[62:63], v[14:15]
	v_mov_b64_e32 v[60:61], v[12:13]
	v_mov_b64_e32 v[58:59], v[10:11]
	v_mov_b64_e32 v[56:57], v[8:9]
	v_mov_b64_e32 v[54:55], v[6:7]
	v_mov_b64_e32 v[52:53], v[4:5]
	s_waitcnt lgkmcnt(0)
	s_barrier
	s_branch .LBB0_943

; __device__ __forceinline__ int opaque_tid() { int t = threadIdx.x; asm volatile("" : "+v"(t)); return t; }
; template <int DK, int MODE, bool OUTF32> ...
;     ...
;     const int tid = opaque_tid(), wave = tid >> 6, lane = tid & 63, c = lane & 31, hi = lane >> 5;
;     const int rg = wave >> 1, kh = wave & 1;
;     const int qw0 = q0 + 32 * rg, qrow = qw0 + c, cw = qw0 >> 6;
;     int t_lo = 0;
;     if (MODE == 1) { t_lo = (q0 >> 6) - 8; if (t_lo < 0) t_lo = 0; }
;     const int t_hi = ((q0 + 127) >> 6) + 1;
;     bf16x8 qf[NKS];
; #pragma unroll
;     for (int s = 0; s < NKS; ++s) qf[s] = *(const bf16x8*)(Qh + (size_t)qrow * DK + 16 * s + 8 * hi);
;     float cq = 0.f;
;     if (MODE == 0) cq = cumh[qrow];
; #pragma unroll
;     for (int s = 0; s < NKS; ++s) asm volatile("" : "+v"(qf[s]));
;     asm volatile("" : "+v"(cq));
;     if (MODE == 1) { for (int i = tid; i < 257; i += NTHR) ((float*)(a_lds + OFF_RB))[i] = relb[i] * LOG2E; }
;     float cso = 0.f;
;     const float* offs = (const float*)(a_lds + OFF_RB);
;     if (MODE == 0) {
;         if (wave == 0) {
;             const float v0 = relb[lane], v1 = relb[64 + lane];
;             float s0 = v0, s1 = v1;
; #pragma unroll
;             for (int d_ = 1; d_ < 64; d_ <<= 1) {
;                 const float t0 = __int_as_float(__builtin_amdgcn_ds_bpermute((lane - d_) * 4, __float_as_int(s0)));
;                 const float t1 = __int_as_float(__builtin_amdgcn_ds_bpermute((lane - d_) * 4, __float_as_int(s1)));
;                 if (lane >= d_) { s0 += t0; s1 += t1; }
;             }
;             const float tot0 = __int_as_float(__builtin_amdgcn_readlane(__float_as_int(s0), 63));
;             ((float*)(a_lds + OFF_RB))[lane] = s0 - v0; ((float*)(a_lds + OFF_RB))[64 + lane] = s1 - v1 + tot0;
;         }
;         __syncthreads();
;         cq += offs[qrow >> 5];
;     }
;     u32x4 kst0, kst1, kst2 = u32x4{0u, 0u, 0u, 0u}, vst0, vst1; f32x4 cst = f32x4{0.f, 0.f, 0.f, 0.f};
;     const int kr0 = tid / KCH, kc0 = tid % KCH, kr1 = (tid + NTHR) / KCH, kc1 = (tid + NTHR) % KCH, kr2 = (tid + 2 * NTHR) / KCH, kc2 = (tid + 2 * NTHR) % KCH;
;     const int vd0 = tid >> 3, vc0 = tid & 7, vd1 = vd0 + 64;
;     const GAS bf16_t* Kg = (const GAS bf16_t*)Kh; const GAS bf16_t* Vg = (const GAS bf16_t*)Vth; const GAS float* cumg = (const GAS float*)cumh;
;     ...
;     A_ISSUE(t_lo); A_WRITE(0);
;     __syncthreads();
.LBB0_955:
	s_andn2_saveexec_b64 s[46:47], s[46:47]
	s_cbranch_execz .LBB0_971
	v_mov_b32_e32 v24, v0
	v_mul_hi_i32_i24_e32 v7, 0xc0000, v156
	v_ashrrev_i32_e32 v2, 2, v24
	v_mul_i32_i24_e32 v6, 0xc0000, v156
	v_and_b32_e32 v2, 0xffffffe0, v2
	v_lshlrev_b64 v[6:7], 1, v[6:7]
	v_and_b32_e32 v25, 31, v24
	v_add_u32_e32 v26, v2, v4
	v_lshl_add_u64 v[8:9], s[18:19], 0, v[6:7]
	v_bfe_u32 v170, v24, 5, 1
	v_or_b32_e32 v154, v26, v25
	v_mad_i64_i32 v[4:5], s[12:13], v154, s69, v[8:9]
	v_lshlrev_b32_e32 v2, 4, v170
	v_lshl_add_u64 v[4:5], v[4:5], 0, v[2:3]
	global_load_dwordx4 v[142:145], v[4:5], off
	global_load_dwordx4 v[138:141], v[4:5], off offset:32
	global_load_dwordx4 v[134:137], v[4:5], off offset:64
	global_load_dwordx4 v[130:133], v[4:5], off offset:96
	global_load_dwordx4 v[126:129], v[4:5], off offset:128
	global_load_dwordx4 v[122:125], v[4:5], off offset:160
	global_load_dwordx4 v[118:121], v[4:5], off offset:192
	global_load_dwordx4 v[114:117], v[4:5], off offset:224
	global_load_dwordx4 v[110:113], v[4:5], off offset:256
	global_load_dwordx4 v[106:109], v[4:5], off offset:288
	global_load_dwordx4 v[102:105], v[4:5], off offset:320
	global_load_dwordx4 v[98:101], v[4:5], off offset:352
	v_ashrrev_i32_e32 v157, 31, v156
	v_lshlrev_b64 v[4:5], 20, v[156:157]
	s_mov_b32 s12, 0x2aaaaaab
	v_lshl_add_u64 v[18:19], s[40:41], 0, v[4:5]
	v_mul_hi_i32 v4, v24, s12
	v_add_u32_e32 v10, 0x200, v24
	v_lshl_add_u64 v[158:159], s[56:57], 0, v[6:7]
	v_lshrrev_b32_e32 v5, 31, v4
	v_ashrrev_i32_e32 v4, 2, v4
	v_mul_hi_i32 v6, v10, s12
	v_add_u32_e32 v11, 0x400, v24
	v_add_u32_e32 v76, v4, v5
	v_lshrrev_b32_e32 v4, 31, v6
	v_ashrrev_i32_e32 v5, 2, v6
	v_ashrrev_i32_e32 v20, 3, v24
	v_mul_hi_i32 v7, v11, s12
	v_add_u32_e32 v77, v5, v4
	v_ashrrev_i32_e32 v21, 31, v20
	v_lshrrev_b32_e32 v6, 31, v7
	v_ashrrev_i32_e32 v7, 2, v7
	v_mul_lo_u32 v8, v76, 24
	v_mul_lo_u32 v12, v77, 24
	v_lshlrev_b64 v[22:23], 13, v[20:21]
	v_add_u32_e32 v78, v7, v6
	v_sub_u32_e32 v21, v24, v8
	v_sub_u32_e32 v27, v10, v12
	v_mul_lo_u32 v13, v78, 24
	v_lshlrev_b32_e32 v10, 3, v21
	v_lshlrev_b32_e32 v12, 3, v27
	v_sub_u32_e32 v28, v11, v13
	v_ashrrev_i32_e32 v11, 31, v10
	v_ashrrev_i32_e32 v13, 31, v12
	v_mad_i64_i32 v[4:5], s[12:13], v76, s69, v[158:159]
	v_mad_i64_i32 v[6:7], s[12:13], v77, s69, v[158:159]
	v_lshlrev_b32_e32 v14, 3, v28
	v_lshlrev_b64 v[70:71], 1, v[10:11]
	v_lshlrev_b64 v[72:73], 1, v[12:13]
	v_mov_b32_e32 v16, v3
	v_ashrrev_i32_e32 v15, 31, v14
	v_lshl_add_u64 v[4:5], v[4:5], 0, v[70:71]
	v_lshl_add_u64 v[6:7], v[6:7], 0, v[72:73]
	v_mad_i64_i32 v[8:9], s[12:13], v78, s69, v[158:159]
	v_lshlrev_b64 v[74:75], 1, v[14:15]
	v_lshl_add_u64 v[8:9], v[8:9], 0, v[74:75]
	v_mov_b32_e32 v161, v3
	s_mov_b32 s12, 0x80000
	v_ashrrev_i32_e32 v157, 6, v24
	s_movk_i32 s13, 0x88
	v_and_b32_e32 v172, 1, v157
	v_mul_lo_u32 v177, v20, s13
	v_mad_u32_u24 v20, v25, s13, 0
	s_movk_i32 s13, 0x190
	s_mov_b64 s[14:15], 0x80080
	v_lshl_or_b32 v25, v172, 5, v25
	v_mul_lo_u32 v180, v76, s13
	v_lshlrev_b32_e32 v183, 4, v21
	global_load_dwordx4 v[34:37], v[4:5], off
	global_load_dwordx4 v[38:41], v[6:7], off
	v_lshlrev_b32_e32 v6, 4, v24
	v_lshl_add_u64 v[4:5], v[18:19], 0, v[22:23]
	v_and_b32_e32 v160, 0x70, v6
	v_lshl_add_u64 v[4:5], v[4:5], 0, v[160:161]
	global_load_dwordx4 v[42:45], v[8:9], off
	global_load_dwordx4 v[46:49], v[4:5], off
	v_add_co_u32_e32 v4, vcc, s12, v4
	v_or_b32_e32 v22, v22, v160
	s_nop 0
	v_addc_co_u32_e32 v5, vcc, 0, v5, vcc
	global_load_dwordx4 v[66:69], v[4:5], off
	v_lshl_add_u64 v[18:19], v[18:19], 0, v[22:23]
	v_add3_u32 v29, 0, v177, v160
	v_lshl_add_u64 v[162:163], v[18:19], 0, s[14:15]
	v_mad_i64_i32 v[70:71], s[14:15], v76, s69, v[70:71]
	v_mad_i64_i32 v[74:75], s[14:15], v78, s69, v[74:75]
	v_mad_i64_i32 v[72:73], s[14:15], v77, s69, v[72:73]
	v_mov_b32_e32 v16, v3
	v_mov_b32_e32 v17, v3
	v_and_b32_e32 v161, 63, v24
	v_lshlrev_b32_e32 v24, 3, v170
	v_lshlrev_b32_e32 v30, 6, v172
	v_add_u32_e32 v79, 0xc800, v29
	v_add_u32_e32 v80, 0xea00, v29
	v_mul_u32_u24_e32 v25, 0x190, v25
	v_mul_lo_u32 v181, v77, s13
	v_mul_lo_u32 v182, v78, s13
	v_add3_u32 v81, 0, v180, v183
	v_lshlrev_b32_e32 v184, 4, v27
	v_lshlrev_b32_e32 v185, 4, v28
	s_mov_b64 s[14:15], 0x6000
	v_mov_b32_e32 v4, v3
	v_mov_b32_e32 v5, v3
	v_mov_b32_e32 v6, v3
	v_mov_b32_e32 v7, v3
	v_mov_b32_e32 v8, v3
	v_mov_b32_e32 v9, v3
	v_mov_b32_e32 v10, v3
	v_mov_b32_e32 v11, v3
	v_mov_b32_e32 v12, v3
	v_mov_b32_e32 v13, v3
	v_mov_b32_e32 v14, v3
	v_mov_b32_e32 v15, v3
	v_ashrrev_i32_e32 v179, 6, v26
	v_add3_u32 v174, v20, v24, v30
	v_add3_u32 v176, 0, v25, v2
	v_mov_b32_e32 v2, v3
	v_mov_b64_e32 v[32:33], v[16:17]
	v_mov_b64_e32 v[64:65], v[16:17]
	v_add3_u32 v82, 0, v181, v184
	v_add3_u32 v83, 0, v182, v185
	v_lshl_add_u64 v[164:165], v[70:71], 0, s[14:15]
	v_lshl_add_u64 v[166:167], v[74:75], 0, s[14:15]
	v_lshl_add_u64 v[168:169], v[72:73], 0, s[14:15]
	s_mov_b32 s12, 0
	v_or_b32_e32 v175, 1, v1
	v_mov_b32_e32 v171, 0
	v_mov_b32_e32 v173, 0xf149f2ca
	s_mov_b64 s[42:43], 0
	v_add_u32_e32 v178, 0x2200, v177
	v_ashrrev_i32_e32 v155, 31, v154
	v_mov_b64_e32 v[30:31], v[14:15]
	v_mov_b64_e32 v[28:29], v[12:13]
	v_mov_b64_e32 v[26:27], v[10:11]
	v_mov_b64_e32 v[24:25], v[8:9]
	v_mov_b64_e32 v[22:23], v[6:7]
	v_mov_b64_e32 v[20:21], v[4:5]
	s_waitcnt vmcnt(4)
	ds_write_b128 v81, v[34:37]
	s_waitcnt vmcnt(3)
	ds_write_b128 v82, v[38:41]
	s_waitcnt vmcnt(2)
	ds_write_b128 v83, v[42:45]
	s_waitcnt vmcnt(1)
	ds_write2_b64 v79, v[46:47], v[48:49] offset1:1
	s_waitcnt vmcnt(0)
	ds_write2_b64 v80, v[66:67], v[68:69] offset1:1
	v_mov_b64_e32 v[48:49], v[16:17]
	v_mov_b64_e32 v[80:81], v[16:17]
	v_mov_b64_e32 v[18:19], v[2:3]
	v_mov_b64_e32 v[62:63], v[14:15]
	v_mov_b64_e32 v[60:61], v[12:13]
	v_mov_b64_e32 v[58:59], v[10:11]
	v_mov_b64_e32 v[56:57], v[8:9]
	v_mov_b64_e32 v[54:55], v[6:7]
	v_mov_b64_e32 v[52:53], v[4:5]
	v_mov_b64_e32 v[50:51], v[2:3]
	s_mov_b64 s[16:17], 0x6000
	v_mov_b64_e32 v[46:47], v[14:15]
	v_mov_b64_e32 v[44:45], v[12:13]
	v_mov_b64_e32 v[42:43], v[10:11]
	v_mov_b64_e32 v[40:41], v[8:9]
	v_mov_b64_e32 v[38:39], v[6:7]
	v_mov_b64_e32 v[36:37], v[4:5]
	v_mov_b64_e32 v[34:35], v[2:3]
	v_mov_b64_e32 v[78:79], v[14:15]
	v_mov_b64_e32 v[76:77], v[12:13]
	v_mov_b64_e32 v[74:75], v[10:11]
	v_mov_b64_e32 v[72:73], v[8:9]
	v_mov_b64_e32 v[70:71], v[6:7]
	v_mov_b64_e32 v[68:69], v[4:5]
	v_mov_b64_e32 v[66:67], v[2:3]
	s_waitcnt lgkmcnt(0)
	s_barrier
	s_branch .LBB0_959

; #define LAS __attribute__((address_space(3)))
;     __device__ __forceinline__ void operator()(f32x4 (&acc)[2][2][4][2], int brow, int bcol, int wr, int wc, int fr, int fq) const {
;     ...
;         if (tid < 256) {
;             float S = 0.f, Q = 0.f;
; #pragma unroll
;             for (int c = 0; c < 8; ++c) {
;                 const unsigned long long v = __hip_atomic_load(sg + c, __ATOMIC_RELAXED, __HIP_MEMORY_SCOPE_AGENT);
;                 S += __uint_as_float((unsigned)v); Q += __uint_as_float((unsigned)(v >> 32));
;             }
;             const float mu = S * (1.f / D), var = fmaxf(Q * (1.f / D) - mu * mu, 0.f);
;             *(LAS f32x2*)((LAS unsigned char*)e_lds + 8192 + tid * 8) = f32x2{mu, rsqrtf(var + LN_EPS)};
;         }
.LBB0_1097:
	s_or_b64 exec, exec, s[44:45]
	s_waitcnt lgkmcnt(0)
	s_barrier
	s_and_saveexec_b64 s[42:43], vcc
	s_cbranch_execz .LBB0_1076
	global_load_dwordx2 v[14:15], v[10:11], off sc1
	global_load_dwordx2 v[18:19], v[10:11], off offset:8 sc1
	global_load_dwordx2 v[244:245], v[10:11], off offset:16 sc1
	global_load_dwordx2 v[246:247], v[10:11], off offset:24 sc1
	global_load_dwordx2 v[250:251], v[10:11], off offset:32 sc1
	global_load_dwordx2 v[252:253], v[10:11], off offset:40 sc1
	global_load_dwordx2 v[254:255], v[10:11], off offset:48 sc1
	global_load_dwordx2 v[10:11], v[10:11], off offset:56 sc1
	s_mov_b32 s12, 0x3a000000
	v_lshl_add_u32 v2, v2, 3, 0
	s_waitcnt vmcnt(7)
	v_add_f32_e32 v14, 0, v14
	v_add_f32_e32 v15, 0, v15
	s_waitcnt vmcnt(6)
	v_add_f32_e32 v14, v14, v18
	v_add_f32_e32 v15, v15, v19
	s_waitcnt vmcnt(5)
	v_add_f32_e32 v14, v14, v244
	v_add_f32_e32 v15, v15, v245
	s_waitcnt vmcnt(4)
	v_add_f32_e32 v14, v14, v246
	v_add_f32_e32 v15, v15, v247
	s_waitcnt vmcnt(3)
	v_add_f32_e32 v14, v14, v250
	v_add_f32_e32 v15, v15, v251
	s_waitcnt vmcnt(2)
	v_add_f32_e32 v14, v14, v252
	v_add_f32_e32 v15, v15, v253
	s_waitcnt vmcnt(1)
	v_add_f32_e32 v14, v14, v254
	v_add_f32_e32 v15, v15, v255
	s_waitcnt vmcnt(0)
	v_add_f32_e32 v10, v14, v10
	v_mul_f32_e32 v10, 0x3a000000, v10
	v_add_f32_e32 v11, v15, v11
	v_mul_f32_e32 v14, v10, v10
	v_fma_f32 v11, v11, s12, -v14
	v_max_f32_e32 v11, 0, v11
	v_add_f32_e32 v11, 0x3727c5ac, v11
	v_cmp_gt_f32_e32 vcc, s33, v11
	v_mul_f32_e32 v14, 0x4b800000, v11
	s_nop 0
	v_cndmask_b32_e32 v11, v11, v14, vcc
	v_rsq_f32_e32 v11, v11
	s_nop 0
	v_mul_f32_e32 v14, 0x45800000, v11
	v_cndmask_b32_e32 v11, v11, v14, vcc
	ds_write_b64 v2, v[10:11] offset:8192
	s_branch .LBB0_1076
